# attention tile loop: back edge rotated (loop-back barrier is the loop head; exit test, carried v_mov and branch moved in front of it; exit path has its own barrier)
# baseline (speedup 1.0000x reference)
.Lmy_att_head:
	s_barrier

.LBB0_844:
	v_cndmask_b32_e64 v178, v108, v229, s[6:7]
	v_mul_f32_e32 v108, 0xbe0293ee, v178
	v_fmamk_f32 v111, v182, 0x3e0293ee, v108
	v_mov_b32_e32 v182, v108
	s_addk_i32 s16, 0x200
	v_fmamk_f32 v109, v180, 0x3e0293ee, v108
	v_fmamk_f32 v110, v181, 0x3e0293ee, v108
	v_fmamk_f32 v112, v183, 0x3e0293ee, v108
	v_fmamk_f32 v113, v184, 0x3e0293ee, v108
	s_waitcnt vmcnt(3)
	v_fmamk_f32 v162, v185, 0x3e0293ee, v108
	v_fmamk_f32 v120, v120, 0x3e0293ee, v108
	v_fmamk_f32 v121, v121, 0x3e0293ee, v108
	v_fmamk_f32 v163, v122, 0x3e0293ee, v108
	v_fmamk_f32 v164, v123, 0x3e0293ee, v108
	v_fmamk_f32 v124, v124, 0x3e0293ee, v108
	v_fmamk_f32 v125, v125, 0x3e0293ee, v108
	v_fmamk_f32 v165, v126, 0x3e0293ee, v108
	v_fmamk_f32 v180, v127, 0x3e0293ee, v108
	v_fmamk_f32 v181, v128, 0x3e0293ee, v108
	v_fmac_f32_e32 v182, 0x3e0293ee, v129
	s_add_u32 s68, s68, 0x80000
	s_waitcnt vmcnt(0)
	v_exp_f32_e32 v175, v109
	v_exp_f32_e32 v177, v110
	v_exp_f32_e32 v173, v111
	v_exp_f32_e32 v176, v112
	v_exp_f32_e32 v172, v113
	v_exp_f32_e32 v174, v162
	v_exp_f32_e32 v170, v120
	v_exp_f32_e32 v171, v121
	v_exp_f32_e32 v167, v163
	v_exp_f32_e32 v169, v164
	v_exp_f32_e32 v166, v124
	v_exp_f32_e32 v168, v125
	v_exp_f32_e32 v163, v165
	v_exp_f32_e32 v165, v180
	v_exp_f32_e32 v162, v181
	v_exp_f32_e32 v164, v182
	s_addc_u32 s69, s69, 0
	v_pk_fma_f32 v[128:129], v[98:99], s[50:51], v[108:109] op_sel_hi:[1,0,0]
	v_add_f32_e32 v98, v226, v227
	s_add_u32 s66, s66, 0x80000
	v_fmac_f32_e32 v98, v225, v224
	v_add_f32_e32 v224, v230, v231
	s_addc_u32 s67, s67, 0
	v_pk_fma_f32 v[126:127], v[114:115], s[50:51], v[108:109] op_sel_hi:[1,0,0]
	v_pk_fma_f32 v[122:123], v[116:117], s[50:51], v[108:109] op_sel_hi:[1,0,0]
	v_pk_fma_f32 v[118:119], v[118:119], s[50:51], v[108:109] op_sel_hi:[1,0,0]
	v_pk_fma_f32 v[114:115], v[106:107], s[50:51], v[108:109] op_sel_hi:[1,0,0]
	v_pk_fma_f32 v[124:125], v[100:101], s[50:51], v[108:109] op_sel_hi:[1,0,0]
	v_pk_fma_f32 v[120:121], v[102:103], s[50:51], v[108:109] op_sel_hi:[1,0,0]
	v_pk_fma_f32 v[116:117], v[104:105], s[50:51], v[108:109] op_sel_hi:[1,0,0]
	v_fmac_f32_e32 v224, v98, v228
	s_cmp_ge_u32 s1, s33
	s_waitcnt lgkmcnt(0)
	s_cbranch_scc1 .Lmy_att_exit
	v_mov_b32_e32 v225, v179
	s_branch .Lmy_att_head
